# attention work queue: first unit of each workgroup claimed statically by block index, later claims offset by the grid size (no 256-way atomic burst at phase start)
# speedup vs baseline: 1.0191x; 1.0191x over previous
; #define LAS __attribute__((address_space(3)))
; __global__ void __launch_bounds__(NTHR) fwd_kernel(Args args) {
;     ...
;             const int* pos = (const int*)ap->in[1];
;             float lam_u;
;             { float a1 = lane < 32 ? ap->in[12][L * 32 + lane] * ap->in[13][L * 32 + lane] : 0.f, a2 = lane < 32 ? ap->in[14][L * 32 + lane] * ap->in[15][L * 32 + lane] : 0.f;
;               a1 = wave_sum(a1); a2 = wave_sum(a2); const float lv = __expf(a1) - __expf(a2) + (L == 0 ? ap->lam_init[0] : ap->lam_init[1]);
;               lam_u = __uint_as_float((unsigned)__builtin_amdgcn_readfirstlane((int)__float_as_uint(lv))); }
;             const bool pos_generic = __builtin_amdgcn_readfirstlane((int)__hip_atomic_load((const unsigned*)(ws + WS_POSFLAG), __ATOMIC_RELAXED, __HIP_MEMORY_SCOPE_AGENT)) != 0 || G > 1024;
;             {
;                 volatile LAS unsigned* qslot = (volatile LAS unsigned*)(lds + LDS_MISC + 64);
;                 unsigned* head = (unsigned*)(ws + WS_ATTQ + 64 * L);
;                 for (;;) {
;                     if (tid == 0) *qslot = __hip_atomic_fetch_add(head, 1u, __ATOMIC_RELAXED, __HIP_MEMORY_SCOPE_AGENT);
;                     __syncthreads();
;                     const int idx = __builtin_amdgcn_readfirstlane((int)*qslot);
;                     __syncthreads();
;                     if (idx >= 1024) break;
.LBB0_149:
	s_or_b64 exec, exec, s[36:37]
	v_and_b32_e32 v0, 64, v216
	v_add_u32_e32 v0, 64, v0
	v_xor_b32_e32 v1, 1, v216
	v_cmp_lt_i32_e32 vcc, v1, v0
	s_add_i32 s4, s18, 10
	s_cmp_lt_u32 s4, 21
	v_cndmask_b32_e32 v1, v216, v1, vcc
	v_lshlrev_b32_e32 v193, 2, v1
	ds_bpermute_b32 v1, v193, v4
	s_movk_i32 s4, 0x128
	s_cselect_b32 s4, s4, 0x12c
	s_add_u32 s4, s0, s4
	s_addc_u32 s5, s1, 0
	s_waitcnt lgkmcnt(0)
	v_add_f32_e32 v1, v4, v1
	v_xor_b32_e32 v4, 2, v216
	v_cmp_lt_i32_e32 vcc, v4, v0
	s_load_dword s4, s[4:5], 0x0
	s_movk_i32 s5, 0x3000
	v_cndmask_b32_e32 v4, v216, v4, vcc
	v_lshlrev_b32_e32 v185, 2, v4
	ds_bpermute_b32 v4, v185, v1
	s_waitcnt lgkmcnt(0)
	v_sub_f32_e64 v224, 1.0, s4
	v_cmp_eq_u32_e64 s[40:41], 0, v192
	v_cmp_eq_u32_e64 s[42:43], 0, v216
	v_add_f32_e32 v1, v1, v4
	v_xor_b32_e32 v4, 4, v216
	v_cmp_lt_i32_e32 vcc, v4, v0
	s_nop 1
	v_cndmask_b32_e32 v4, v216, v4, vcc
	v_lshlrev_b32_e32 v220, 2, v4
	ds_bpermute_b32 v4, v220, v1
	s_waitcnt lgkmcnt(0)
	v_add_f32_e32 v1, v1, v4
	v_xor_b32_e32 v4, 8, v216
	v_cmp_lt_i32_e32 vcc, v4, v0
	s_nop 1
	v_cndmask_b32_e32 v4, v216, v4, vcc
	v_lshlrev_b32_e32 v221, 2, v4
	ds_bpermute_b32 v4, v221, v1
	s_waitcnt lgkmcnt(0)
	v_add_f32_e32 v1, v1, v4
	v_xor_b32_e32 v4, 16, v216
	v_cmp_lt_i32_e32 vcc, v4, v0
	s_nop 1
	v_cndmask_b32_e32 v4, v216, v4, vcc
	v_lshlrev_b32_e32 v222, 2, v4
	ds_bpermute_b32 v4, v222, v1
	s_waitcnt lgkmcnt(0)
	v_add_f32_e32 v1, v1, v4
	v_xor_b32_e32 v4, 32, v216
	v_cmp_lt_i32_e32 vcc, v4, v0
	s_nop 1
	v_cndmask_b32_e32 v0, v216, v4, vcc
	v_lshlrev_b32_e32 v223, 2, v0
	ds_bpermute_b32 v0, v223, v1
	s_waitcnt lgkmcnt(0)
	v_add_f32_e32 v0, v1, v0
	ds_bpermute_b32 v1, v193, v2
	v_mul_f32_e32 v0, 0x3fb8aa3b, v0
	v_exp_f32_e32 v0, v0
	s_waitcnt lgkmcnt(0)
	v_add_f32_e32 v1, v2, v1
	ds_bpermute_b32 v2, v185, v1
	s_waitcnt lgkmcnt(0)
	v_add_f32_e32 v1, v1, v2
	ds_bpermute_b32 v2, v220, v1
	s_waitcnt lgkmcnt(0)
	v_add_f32_e32 v1, v1, v2
	ds_bpermute_b32 v2, v221, v1
	s_waitcnt lgkmcnt(0)
	v_add_f32_e32 v1, v1, v2
	ds_bpermute_b32 v2, v222, v1
	s_waitcnt lgkmcnt(0)
	v_add_f32_e32 v1, v1, v2
	ds_bpermute_b32 v2, v223, v1
	s_waitcnt lgkmcnt(0)
	v_add_f32_e32 v1, v1, v2
	v_mul_f32_e32 v1, 0x3fb8aa3b, v1
	v_exp_f32_e32 v1, v1
	s_nop 0
	v_sub_f32_e32 v0, v0, v1
	v_add_f32_e32 v0, s4, v0
	v_mov_b32_e32 v1, s73
	v_readfirstlane_b32 s2, v0
	v_mov_b32_e32 v0, s72
	v_add_co_u32_e32 v0, vcc, s5, v0
	v_writelane_b32 v255, s2, 19
	s_nop 0
	v_addc_co_u32_e32 v1, vcc, 0, v1, vcc
	flat_load_dword v0, v[0:1] offset:3072 sc1
	s_waitcnt vmcnt(0) lgkmcnt(0)
	v_readfirstlane_b32 s5, v0
	s_cmp_eq_u32 s5, 0
	s_cselect_b64 s[18:19], -1, 0
	s_cmpk_lt_i32 s85, 0x401
	s_cselect_b64 s[26:27], -1, 0
	s_lshl_b32 s36, s10, 6
	s_and_b64 s[28:29], s[18:19], s[26:27]
	s_ashr_i32 s37, s36, 31
	s_add_u32 s5, s72, s36
	s_addc_u32 s6, s73, s37
	s_add_u32 s58, s5, 0x3800
	s_addc_u32 s59, s6, 0
	s_add_u32 s50, s72, 0x7400000
	s_addc_u32 s51, s73, 0
	s_add_u32 s25, s72, 0x7400400
	s_addc_u32 s52, s73, 0
	s_add_u32 s5, s72, 0x9400000
	v_writelane_b32 v255, s5, 17
	s_addc_u32 s5, s73, 0
	s_add_u32 s18, s72, 0xb100000
	s_addc_u32 s19, s73, 0
	s_ashr_i32 s11, s10, 31
	s_lshl_b64 s[38:39], s[10:11], 17
	s_add_u32 s64, s72, 0xc100000
	s_addc_u32 s65, s73, 0
	s_add_u32 s75, s72, 0xd900000
	s_addc_u32 s53, s73, 0
	s_add_u32 s2, s72, 0xb000000
	s_addc_u32 s92, s73, 0
	s_add_u32 s56, s72, 0xe900000
	s_addc_u32 s93, s73, 0
	s_add_u32 s62, s72, 0x6400000
	s_addc_u32 s63, s73, 0
	s_add_u32 s66, s72, 0xc0000
	s_addc_u32 s67, s73, 0
	v_writelane_b32 v255, s5, 18
	s_add_u32 s4, s72, s38
	v_writelane_b32 v255, s18, 20
	s_addc_u32 s5, s73, s39
	s_add_u32 s4, s4, 0x3340004
	v_writelane_b32 v255, s19, 21
	v_writelane_b32 v255, s4, 22
	s_addc_u32 s4, s5, 0
	v_writelane_b32 v255, s4, 23
	s_add_u32 s4, s54, 0x200
	v_writelane_b32 v255, s4, 24
	s_addc_u32 s4, s55, 0
	v_writelane_b32 v255, s4, 25
	s_lshl_b64 s[36:37], s[36:37], 2
	v_writelane_b32 v255, s25, 26
	v_writelane_b32 v255, s36, 27
	s_nop 1
	v_writelane_b32 v255, s37, 28
	v_readlane_b32 s38, v255, 4
	s_mov_b64 s[44:45], -1
	s_nop 0
	s_cmpk_gt_i32 s38, 0x3ff
	s_cbranch_scc1 .LBB0_153
	s_branch .Lq_first

; __global__ void __launch_bounds__(NTHR) fwd_kernel(Args args) {
;     ...
;                     if (tid == 0) *qslot = __hip_atomic_fetch_add(head, 1u, __ATOMIC_RELAXED, __HIP_MEMORY_SCOPE_AGENT);
;                     __syncthreads();
;                     const int idx = __builtin_amdgcn_readfirstlane((int)*qslot);
;                     __syncthreads();
;                     if (idx >= 1024) break;
.LBB0_156:
	s_or_b64 exec, exec, s[38:39]
	v_mov_b32_e32 v0, s95
	s_waitcnt lgkmcnt(0)
	s_barrier
	ds_read_b32 v0, v0
	s_mov_b64 s[44:45], -1
	s_waitcnt lgkmcnt(0)
	s_barrier
	v_readfirstlane_b32 s38, v0
	v_readlane_b32 s39, v254, 0
	s_nop 0
	s_add_i32 s38, s38, s39
	s_cmpk_gt_i32 s38, 0x3ff
	s_cbranch_scc1 .LBB0_153
; template <int MODE, bool FAST = false> __device__ __forceinline__ void attn_unit(LAS unsigned char* lds, const P& A, int b, int h, int qb) {
;     ...
;         { const bf16* qs = A.Q + (size_t)(rowbase + qrow) * 1024 + h * 64 + 8 * hi;
; #pragma unroll
;           for (int d0 = 0; d0 < 4; ++d0) { const u32x4 raw = *(const u32x4*)(qs + 16 * d0); u32x4 wv;
; #pragma unroll
;               for (int e = 0; e < 4; ++e) wv[e] = cvt_pk_bf16(bf_lo(raw[e]) * qscale, bf_hi(raw[e]) * qscale);
;               qr[d0] = __builtin_bit_cast(bf16x8, wv); } }
;         float bq0 = 0.f, bq1 = 0.f;
;         if constexpr (FAST) {
;             float n0 = 0.f, n1 = 0.f;
; #pragma unroll
;             for (int d0 = 0; d0 < 4; ++d0) { const u32x4 qv = __builtin_bit_cast(u32x4, qr[d0]); float a = 0.f;
; #pragma unroll
;                 for (int e = 0; e < 4; ++e) { const float x = bf_lo(qv[e]), y = bf_hi(qv[e]); a += x * x + y * y; }
;                 if (d0 < 2) n0 += a; else n1 += a; }
;             n0 += __shfl_xor(n0, 32); n1 += __shfl_xor(n1, 32);
;             float k0 = 0.f, k1 = 0.f; const float* km = A.kmax + (b * 16 + h * 2);
; __global__ void __launch_bounds__(NTHR) fwd_kernel(Args args) {
;     ...
;                     const int code = ap->order[idx], type = code >> 9, b = (code >> 8) & 1, h = (code >> 5) & 7, qb = code & 31;
;                     if (type == 0) {
;     ...
;                         att::P A{}; A.Q = (const bf16*)(ws + WS_QM); A.qpitch = 768; A.K = (const bf16*)(ws + WS_KN) + h * 64; A.kpitch = 512; A.KR = (const bf16*)(ws + WS_KR);
;                         A.V = (const bf16*)(ws + WS_VTM); A.vpitch = 0; A.O = (bf16*)(ws + WS_OM); A.pos = pos; A.invf = (const float*)(ws + WS_TAB);
;                         att::attn_unit<0>(lds, A, b, h, qb);
;     ...
;                     } else {
;     ...
;                         att::P A{}; A.Q = (const bf16*)(ws + WS_Z2); A.qpitch = 1024; A.K = (const bf16*)(ws + WS_Z2) + 512 + h * 64; A.kpitch = 1024; A.V = (const bf16*)(ws + WS_VTD); A.vpitch = 0;
;                         A.O = (bf16*)(ws + WS_OD); A.pos = pos; A.subln = ap->in[16] + L * 64; A.lam = lam_u; A.kmax = (const float*)(ws + WS_KMAX) + (size_t)L * 1024 * 32; A.nblk = G;
;                         A.lam_init = L == 0 ? ap->lam_init[0] : ap->lam_init[1];
;                         if (pos_generic) att::attn_unit<1, false>(lds, A, b, h, qb); else att::attn_unit<1, true>(lds, A, b, h, qb);
.Lq_first:
	s_ashr_i32 s39, s38, 31
	s_lshl_b64 s[4:5], s[38:39], 1
	s_add_u32 s4, s0, s4
	s_addc_u32 s5, s1, s5
	global_load_ushort v0, v3, s[4:5] offset:312
	s_movk_i32 s4, 0x1ff
	s_mov_b64 s[38:39], -1
	s_waitcnt vmcnt(0)
	v_readfirstlane_b32 s20, v0
	v_cmp_lt_u32_e32 vcc, s4, v0
	s_bfe_u32 s69, s20, 0x30005
	s_lshr_b32 s57, s20, 8
	s_and_b32 s97, s20, 31
	s_lshl_b32 s11, s69, 6
	s_cbranch_vccz .LBB0_239
	s_load_dwordx2 s[26:27], s[0:1], 0x80
	s_and_b32 s5, s57, 1
	s_lshl_b32 s6, s11, 1
	s_add_u32 s15, s25, s6
	s_addc_u32 s18, s52, 0
	s_waitcnt lgkmcnt(0)
	s_add_u32 s70, s26, s36
	s_addc_u32 s71, s27, s37
	s_lshl_b32 s12, s97, 8
	s_lshl_b32 s4, s5, 13
	s_and_b64 vcc, exec, s[28:29]
	s_cbranch_vccz .LBB0_225
	v_mov_b32_e32 v2, v184
	v_mov_b32_e32 v195, v3
	v_readfirstlane_b32 s19, v2
	s_ashr_i32 s19, s19, 1
	s_and_b32 s25, s19, 0xffffffe0
	s_add_i32 s25, s25, s12
	v_and_or_b32 v8, v2, 31, s25
	v_add_u32_e32 v194, s4, v8
	v_lshlrev_b64 v[0:1], 11, v[194:195]
	v_bfe_u32 v208, v2, 5, 1
	v_lshl_add_u64 v[0:1], s[50:51], 0, v[0:1]
	v_lshl_add_u64 v[0:1], v[0:1], 0, s[6:7]
	v_lshlrev_b32_e32 v196, 4, v208
	v_mov_b32_e32 v197, v3
	v_lshl_add_u64 v[0:1], v[0:1], 0, v[196:197]
	flat_load_dwordx4 v[10:13], v[0:1]
	s_mov_b32 s26, 0x3e8293ee
	v_and_b32_e32 v4, 63, v2
	v_cmp_gt_i32_e32 vcc, s85, v4
	s_waitcnt vmcnt(0) lgkmcnt(0)
	v_lshlrev_b32_e32 v6, 16, v10
	v_and_b32_e32 v7, 0xffff0000, v10
	v_pk_mul_f32 v[6:7], v[6:7], s[26:27] op_sel_hi:[1,0]
	s_nop 0
	v_cvt_pk_bf16_f32 v144, v6, v7
	v_lshlrev_b32_e32 v6, 16, v11
	v_and_b32_e32 v7, 0xffff0000, v11
	v_pk_mul_f32 v[6:7], v[6:7], s[26:27] op_sel_hi:[1,0]
	s_nop 0
	v_cvt_pk_bf16_f32 v145, v6, v7
	v_lshlrev_b32_e32 v6, 16, v12
	v_and_b32_e32 v7, 0xffff0000, v12
	v_pk_mul_f32 v[6:7], v[6:7], s[26:27] op_sel_hi:[1,0]
	v_and_b32_e32 v5, 0xffff0000, v145
	v_cvt_pk_bf16_f32 v146, v6, v7
	v_lshlrev_b32_e32 v6, 16, v13
	v_and_b32_e32 v7, 0xffff0000, v13
	flat_load_dwordx4 v[10:13], v[0:1] offset:32
	v_pk_mul_f32 v[6:7], v[6:7], s[26:27] op_sel_hi:[1,0]
	v_mul_f32_e32 v5, v5, v5
	v_cvt_pk_bf16_f32 v147, v6, v7
	s_waitcnt vmcnt(0) lgkmcnt(0)
	v_lshlrev_b32_e32 v6, 16, v10
	v_and_b32_e32 v7, 0xffff0000, v10
	v_pk_mul_f32 v[6:7], v[6:7], s[26:27] op_sel_hi:[1,0]
	s_nop 0
	v_cvt_pk_bf16_f32 v148, v6, v7
	v_lshlrev_b32_e32 v6, 16, v11
	v_and_b32_e32 v7, 0xffff0000, v11
	v_pk_mul_f32 v[6:7], v[6:7], s[26:27] op_sel_hi:[1,0]
	s_nop 0
	v_cvt_pk_bf16_f32 v149, v6, v7
	v_lshlrev_b32_e32 v6, 16, v12
	v_and_b32_e32 v7, 0xffff0000, v12
	v_pk_mul_f32 v[6:7], v[6:7], s[26:27] op_sel_hi:[1,0]
	s_nop 0
	v_cvt_pk_bf16_f32 v150, v6, v7
	v_lshlrev_b32_e32 v6, 16, v13
	v_and_b32_e32 v7, 0xffff0000, v13
	flat_load_dwordx4 v[10:13], v[0:1] offset:64
	v_pk_mul_f32 v[6:7], v[6:7], s[26:27] op_sel_hi:[1,0]
	s_nop 0
	v_cvt_pk_bf16_f32 v151, v6, v7
	s_waitcnt vmcnt(0) lgkmcnt(0)
	v_lshlrev_b32_e32 v6, 16, v10
	v_and_b32_e32 v7, 0xffff0000, v10
	v_pk_mul_f32 v[6:7], v[6:7], s[26:27] op_sel_hi:[1,0]
	s_nop 0
	v_cvt_pk_bf16_f32 v152, v6, v7
	v_lshlrev_b32_e32 v6, 16, v11
	v_and_b32_e32 v7, 0xffff0000, v11
	v_pk_mul_f32 v[6:7], v[6:7], s[26:27] op_sel_hi:[1,0]
	s_nop 0
	v_cvt_pk_bf16_f32 v153, v6, v7
	v_lshlrev_b32_e32 v6, 16, v12
	v_and_b32_e32 v7, 0xffff0000, v12
	v_pk_mul_f32 v[6:7], v[6:7], s[26:27] op_sel_hi:[1,0]
	s_nop 0
	v_cvt_pk_bf16_f32 v154, v6, v7
	v_lshlrev_b32_e32 v6, 16, v13
	v_and_b32_e32 v7, 0xffff0000, v13
	flat_load_dwordx4 v[10:13], v[0:1] offset:96
	v_pk_mul_f32 v[6:7], v[6:7], s[26:27] op_sel_hi:[1,0]
	s_waitcnt vmcnt(0) lgkmcnt(0)
	v_lshlrev_b32_e32 v0, 16, v10
	v_and_b32_e32 v1, 0xffff0000, v10
	v_pk_mul_f32 v[0:1], v[0:1], s[26:27] op_sel_hi:[1,0]
	v_cvt_pk_bf16_f32 v155, v6, v7
	v_cvt_pk_bf16_f32 v156, v0, v1
	v_lshlrev_b32_e32 v0, 16, v11
	v_and_b32_e32 v1, 0xffff0000, v11
	v_pk_mul_f32 v[0:1], v[0:1], s[26:27] op_sel_hi:[1,0]
	v_and_b32_e32 v6, 0xffff0000, v149
	v_cvt_pk_bf16_f32 v157, v0, v1
	v_lshlrev_b32_e32 v0, 16, v12
	v_and_b32_e32 v1, 0xffff0000, v12
	v_pk_mul_f32 v[0:1], v[0:1], s[26:27] op_sel_hi:[1,0]
	v_mul_f32_e32 v6, v6, v6
	v_cvt_pk_bf16_f32 v158, v0, v1
	v_lshlrev_b32_e32 v0, 16, v13
	v_and_b32_e32 v1, 0xffff0000, v13
	v_pk_mul_f32 v[0:1], v[0:1], s[26:27] op_sel_hi:[1,0]
	s_nop 0
	v_cvt_pk_bf16_f32 v159, v0, v1
	v_and_b32_e32 v1, 0xffff0000, v144
	v_lshlrev_b32_e32 v0, 16, v144
	v_mul_f32_e32 v1, v1, v1
	v_fmac_f32_e32 v1, v0, v0
	v_lshlrev_b32_e32 v0, 16, v145
	v_fmac_f32_e32 v5, v0, v0
	v_add_f32_e32 v0, v1, v5
	v_and_b32_e32 v5, 0xffff0000, v146
	v_lshlrev_b32_e32 v1, 16, v146
	v_mul_f32_e32 v5, v5, v5
	v_fmac_f32_e32 v5, v1, v1
	v_add_f32_e32 v0, v5, v0
	v_and_b32_e32 v5, 0xffff0000, v147
	v_lshlrev_b32_e32 v1, 16, v147
	v_mul_f32_e32 v5, v5, v5
	v_fmac_f32_e32 v5, v1, v1
	v_add_f32_e32 v0, v5, v0
	v_and_b32_e32 v5, 0xffff0000, v148
	v_lshlrev_b32_e32 v1, 16, v148
	v_mul_f32_e32 v5, v5, v5
	v_fmac_f32_e32 v5, v1, v1
	v_lshlrev_b32_e32 v1, 16, v149
	v_fmac_f32_e32 v6, v1, v1
	v_add_f32_e32 v1, v5, v6
	v_and_b32_e32 v6, 0xffff0000, v150
	v_lshlrev_b32_e32 v5, 16, v150
	v_mul_f32_e32 v6, v6, v6
	v_fmac_f32_e32 v6, v5, v5
	v_add_f32_e32 v1, v6, v1
	v_and_b32_e32 v6, 0xffff0000, v151
	v_lshlrev_b32_e32 v5, 16, v151
	v_mul_f32_e32 v6, v6, v6
	v_fmac_f32_e32 v6, v5, v5
	v_add_f32_e32 v1, v6, v1
	v_add_f32_e32 v9, v0, v1
	v_and_b32_e32 v1, 0xffff0000, v152
	v_lshlrev_b32_e32 v0, 16, v152
	v_mul_f32_e32 v1, v1, v1
	v_and_b32_e32 v5, 0xffff0000, v153
	v_fmac_f32_e32 v1, v0, v0
	v_lshlrev_b32_e32 v0, 16, v153
	v_mul_f32_e32 v5, v5, v5
	v_fmac_f32_e32 v5, v0, v0
	v_add_f32_e32 v0, v1, v5
	v_and_b32_e32 v5, 0xffff0000, v154
	v_lshlrev_b32_e32 v1, 16, v154
	v_mul_f32_e32 v5, v5, v5
	v_fmac_f32_e32 v5, v1, v1
	v_add_f32_e32 v0, v5, v0
	v_and_b32_e32 v5, 0xffff0000, v155
	v_lshlrev_b32_e32 v1, 16, v155
	v_mul_f32_e32 v5, v5, v5
	v_fmac_f32_e32 v5, v1, v1
	v_add_f32_e32 v0, v5, v0
	v_and_b32_e32 v5, 0xffff0000, v156
	v_lshlrev_b32_e32 v1, 16, v156
	v_mul_f32_e32 v5, v5, v5
	v_and_b32_e32 v6, 0xffff0000, v157
	v_fmac_f32_e32 v5, v1, v1
	v_lshlrev_b32_e32 v1, 16, v157
	v_mul_f32_e32 v6, v6, v6
	v_fmac_f32_e32 v6, v1, v1
	v_add_f32_e32 v1, v5, v6
	v_and_b32_e32 v6, 0xffff0000, v158
	v_lshlrev_b32_e32 v5, 16, v158
	v_mul_f32_e32 v6, v6, v6
	v_fmac_f32_e32 v6, v5, v5
	v_add_f32_e32 v1, v6, v1
	v_and_b32_e32 v6, 0xffff0000, v159
	v_lshlrev_b32_e32 v5, 16, v159
	v_mul_f32_e32 v6, v6, v6
	v_fmac_f32_e32 v6, v5, v5
	v_add_f32_e32 v1, v6, v1
	v_add_f32_e32 v10, v0, v1
	ds_bpermute_b32 v11, v223, v9
	ds_bpermute_b32 v12, v223, v10
	v_mov_b32_e32 v5, 0
	v_mov_b32_e32 v6, 0
	s_and_saveexec_b64 s[38:39], vcc
	s_cbranch_execz .LBB0_163
	s_lshl_b32 s19, s69, 3
	s_lshl_b32 s23, s5, 6
	s_or_b32 s19, s23, s19
	v_readlane_b32 s23, v255, 22
	v_and_b32_e32 v0, 63, v2
	s_add_u32 s26, s23, s19
	v_readlane_b32 s19, v255, 23
	v_lshlrev_b32_e32 v2, 7, v0
	s_addc_u32 s27, s19, 0
	v_lshl_add_u64 v[0:1], s[26:27], 0, v[2:3]
	v_mov_b32_e32 v5, 0
	s_mov_b64 s[44:45], 0
	v_mov_b32_e32 v6, 0
